# tile-scheduler headers of P2 and P8: per-unit division by the group size (always 4 for 64 row tiles) replaced by a shift; 26 instructions incl. the v_rcp/readfirstlane chain removed per unit
# speedup vs baseline: 1.0041x; 1.0041x over previous
;     __device__ __forceinline__ bool next(int i, Unit& u) const { if (!base.next(i >> 1, u)) return false; if (i & 1) { u.pm += 64; u.pn += 8; } return true; }
;     __device__ bool next(int i, Unit& u) const {
;         const long L = (long)i * G + c; if (L >= nwg) return false;
;         int wgid = (int)L; { const int q = nwg / NXCD, r = nwg % NXCD, xcd = wgid % NXCD, off = wgid / NXCD; wgid = (xcd < r ? xcd * (q + 1) : r * (q + 1) + (xcd - r) * q) + off; }
;         const int nig = WG * nN, gid = wgid / nig, fm = gid * WG, gsz = (nM - fm) < WG ? (nM - fm) : WG;
;         u.pm = fm + ((wgid % nig) % gsz); u.pn = (wgid % nig) / gsz; return true;
;     __device__ __forceinline__ bool next(int i, Unit& u) const { if (!base.next(i, u)) return false; const int p = u.pn;
;         u.pn = p < 16 ? 22 + p : p < 20 ? p - 16 : p < 24 ? p - 20 + 12 : p < 28 ? p - 24 + 4 : p < 32 ? p - 28 + 8 : p - 32 + 16; return true; }
.LBB0_199:
	s_add_i32 s37, s37, 1
	s_mul_i32 s1, s37, s40
	s_mul_hi_u32 s3, s37, s41
	s_add_i32 s3, s3, s1
	s_mul_i32 s1, s37, s41
	s_add_u32 s24, s1, s55
	s_addc_u32 s25, s3, s42
	v_cmp_gt_i64_e32 vcc, s[24:25], v[178:179]
	v_cmp_lt_i64_e64 s[8:9], s[24:25], v[176:177]
	s_cbranch_vccnz .LBB0_204
	s_ashr_i32 s1, s24, 31
	s_lshr_b32 s1, s1, 29
	s_add_i32 s1, s24, s1
	s_ashr_i32 s3, s1, 3
	s_and_b32 s1, s1, -8
	s_sub_i32 s1, s24, s1
	s_cmp_lt_i32 s1, 0
	s_movk_i32 s20, 0x131
	s_cselect_b32 s20, s20, 0x130
	s_mul_i32 s1, s1, s20
	s_add_i32 s20, s1, s3
	s_mul_hi_i32 s1, s20, 0x6bca1af3
	s_lshr_b32 s3, s1, 31
	s_ashr_i32 s1, s1, 6
	s_add_i32 s21, s1, s3
	s_lshl_b32 s1, s21, 2
	s_sub_i32 s3, 64, s1
	s_min_i32 s3, s3, 4
	s_mulk_i32 s21, 0x98
	s_sub_i32 s20, s20, s21
	s_ashr_i32 s21, s20, 2
	s_cmp_lt_i32 s21, 16
	s_mov_b32 s22, 22
	s_cbranch_scc1 .LBB0_203
	s_cmp_lt_u32 s21, 20
	s_mov_b32 s22, -16
	s_cbranch_scc1 .LBB0_203
	s_cmp_lt_u32 s21, 32
	s_cselect_b32 s22, 0xffffffec, -16
	s_cmp_gt_u32 s21, 23
	s_cselect_b32 s22, s22, -8

;     __device__ __forceinline__ bool next(int i, Unit& u) const { if (!base.next(i >> 1, u)) return false; if (i & 1) { u.pm += 64; u.pn += 8; } return true; }
;     __device__ bool next(int i, Unit& u) const {
;         const long L = (long)i * G + c; if (L >= nwg) return false;
;         int wgid = (int)L; { const int q = nwg / NXCD, r = nwg % NXCD, xcd = wgid % NXCD, off = wgid / NXCD; wgid = (xcd < r ? xcd * (q + 1) : r * (q + 1) + (xcd - r) * q) + off; }
;         const int nig = WG * nN, gid = wgid / nig, fm = gid * WG, gsz = (nM - fm) < WG ? (nM - fm) : WG;
;         u.pm = fm + ((wgid % nig) % gsz); u.pn = (wgid % nig) / gsz; return true;
.LBB0_1069:
	s_ashr_i32 s16, s18, 3
	s_add_i32 s16, s20, s16
	s_ashr_i32 s17, s16, 31
	s_lshr_b32 s17, s17, 27
	s_add_i32 s17, s16, s17
	s_ashr_i32 s18, s17, 5
	s_lshl_b32 s18, s18, 2
	s_xor_b32 s18, s18, 4
	s_sub_i32 s19, 64, s18
	s_min_i32 s19, s19, 4
	s_andn2_b32 s17, s17, 31
	s_sub_i32 s17, s16, s17
	s_ashr_i32 s16, s17, 2
	s_mul_i32 s19, s16, s19
	s_sub_i32 s17, s17, s19
	s_add_i32 s18, s18, s17
